# final RMSNorm loop hand-written (gamma hoisted, no serialized load-wait-store ladder); HGRN2 pass-2 chunk loop: LDS operand reads for the state-update and output MFMAs issued ahead through a ring of B
# speedup vs baseline: 1.0197x; 1.0033x over previous
; __device__ __forceinline__ bf16_t f2bf(float f) { return (bf16_t)(cvt_pk_bf16(f, 0.f) & 0xffffu); }
; __device__ __forceinline__ void lds_barrier() { asm volatile("s_waitcnt lgkmcnt(0)\n\ts_barrier" ::: "memory"); }
; __device__ __forceinline__ void hg2_unit(KP p, int u, unsigned char* shm, int tid) {
;     ...
;       for (int j = 0; j < 4; ++j) { const int t = mt * 16 + fq * 4 + j, sl = nt * 16 + fr; AM[t * 72 + sl] = f2bf(sl <= t ? acc[j] : 0.f); }
;     }
;     lds_barrier();
;     {
;       const int mt = wv & 3, nb = (wv >> 2) * 4;
;       f32x4 oacc[4];
; #pragma unroll
;       for (int x = 0; x < 4; ++x) oacc[x] = (f32x4){0.f, 0.f, 0.f, 0.f};
; #pragma unroll
;       for (int ks = 0; ks < 2; ++ks) {
;         const bf16x8 a = *(const bf16x8*)(AM + (mt * 16 + fr) * 72 + ks * 32 + fq * 8);
; #pragma unroll
;         for (int x = 0; x < 4; ++x) { const bf16x8 b = *(const bf16x8*)(VT + ((nb + x) * 16 + fr) * 72 + ks * 32 + fq * 8); oacc[x] = __builtin_amdgcn_mfma_f32_16x16x32_bf16(a, b, oacc[x], 0, 0, 0); }
;       }
; #pragma unroll
;       for (int ks = 0; ks < 4; ++ks) {
;         const bf16x8 a = *(const bf16x8*)(QIN + (mt * 16 + fr) * 136 + ks * 32 + fq * 8);
; #pragma unroll
;         for (int x = 0; x < 4; ++x) { const bf16x8 b = *(const bf16x8*)(ST + ((nb + x) * 16 + fr) * 136 + ks * 32 + fq * 8); oacc[x] = __builtin_amdgcn_mfma_f32_16x16x32_bf16(a, b, oacc[x], 0, 0, 0); }
;       }
.LBB0_80:
	s_or_b64 exec, exec, s[38:39]
	s_nop 5
	v_cndmask_b32_e64 v32, v32, 0, s[2:3]
	v_cvt_pk_bf16_f32 v32, v32, v139
	ds_write_b16 v91, v32
	v_cndmask_b32_e64 v32, v33, 0, s[28:29]
	v_cvt_pk_bf16_f32 v32, v32, v139
	ds_write_b16 v91, v32 offset:144
	v_cndmask_b32_e64 v32, v34, 0, s[30:31]
	v_cvt_pk_bf16_f32 v32, v32, v139
	ds_write_b16 v91, v32 offset:288
	v_cndmask_b32_e64 v32, v35, 0, s[0:1]
	s_waitcnt vmcnt(42)
	v_lshlrev_b32_e32 v72, 16, v128
	s_waitcnt vmcnt(36)
	v_lshlrev_b32_e32 v74, 16, v134
	v_cvt_pk_bf16_f32 v32, v32, v139
	ds_write_b16 v91, v32 offset:432
	v_lshlrev_b32_e32 v37, 16, v127
	v_or_b32_sdwa v115, v72, v126 dst_sel:DWORD dst_unused:UNUSED_PAD src0_sel:DWORD src1_sel:WORD_0
	v_lshlrev_b32_e32 v72, 16, v130
	v_lshlrev_b32_e32 v73, 16, v132
	v_or_b32_sdwa v119, v74, v133 dst_sel:DWORD dst_unused:UNUSED_PAD src0_sel:DWORD src1_sel:WORD_0
	s_waitcnt vmcnt(34)
	v_lshlrev_b32_e32 v74, 16, v136
	s_waitcnt vmcnt(29)
	v_lshlrev_b32_e32 v76, 16, v148
	s_waitcnt vmcnt(26)
	v_lshlrev_b32_e32 v77, 16, v151
	s_waitcnt lgkmcnt(0)
	s_barrier
	v_lshlrev_b32_e32 v36, 16, v124
	v_or_b32_sdwa v37, v37, v125 dst_sel:DWORD dst_unused:UNUSED_PAD src0_sel:DWORD src1_sel:WORD_0
	v_or_b32_sdwa v72, v72, v129 dst_sel:DWORD dst_unused:UNUSED_PAD src0_sel:DWORD src1_sel:WORD_0
	v_or_b32_sdwa v73, v73, v131 dst_sel:DWORD dst_unused:UNUSED_PAD src0_sel:DWORD src1_sel:WORD_0
	v_or_b32_sdwa v74, v74, v135 dst_sel:DWORD dst_unused:UNUSED_PAD src0_sel:DWORD src1_sel:WORD_0
	v_or_b32_sdwa v121, v76, v145 dst_sel:DWORD dst_unused:UNUSED_PAD src0_sel:DWORD src1_sel:WORD_0
	v_lshlrev_b32_e32 v76, 16, v150
	v_or_b32_sdwa v77, v77, v149 dst_sel:DWORD dst_unused:UNUSED_PAD src0_sel:DWORD src1_sel:WORD_0
	ds_read_b128 v[32:35], v92
	ds_read_b128 v[124:127], v100 offset:53248
	ds_read_b128 v[128:131], v101 offset:53248
	ds_read_b128 v[132:135], v102 offset:53248
	ds_read_b128 v[148:151], v103 offset:53248
	s_waitcnt vmcnt(24)
	v_lshlrev_b32_e32 v78, 16, v154
	v_or_b32_sdwa v120, v78, v152 dst_sel:DWORD dst_unused:UNUSED_PAD src0_sel:DWORD src1_sel:WORD_0
	s_waitcnt vmcnt(22)
	v_lshlrev_b32_e32 v78, 16, v156
	s_waitcnt vmcnt(20)
	v_lshlrev_b32_e32 v80, 16, v157
	v_or_b32_sdwa v78, v78, v153 dst_sel:DWORD dst_unused:UNUSED_PAD src0_sel:DWORD src1_sel:WORD_0
	v_or_b32_sdwa v80, v80, v155 dst_sel:DWORD dst_unused:UNUSED_PAD src0_sel:DWORD src1_sel:WORD_0
	s_waitcnt lgkmcnt(3)
	v_mfma_f32_16x16x32_bf16 v[124:127], v[32:35], v[124:127], 0
	v_or_b32_sdwa v36, v36, v123 dst_sel:DWORD dst_unused:UNUSED_PAD src0_sel:DWORD src1_sel:WORD_0
	v_add_u32_e32 v123, s69, v70
	v_add_u32_e32 v136, 0x3fff, v123
	s_waitcnt lgkmcnt(2)
	v_mfma_f32_16x16x32_bf16 v[128:131], v[32:35], v[128:131], 0
	v_lshlrev_b32_e32 v75, 16, v142
	v_cndmask_b32_e64 v136, v136, v71, s[36:37]
	v_or_b32_sdwa v75, v75, v137 dst_sel:DWORD dst_unused:UNUSED_PAD src0_sel:DWORD src1_sel:WORD_0
	s_waitcnt lgkmcnt(1)
	v_mfma_f32_16x16x32_bf16 v[132:135], v[32:35], v[132:135], 0
	v_ashrrev_i32_e32 v137, 31, v136
	v_lshlrev_b64 v[136:137], 11, v[136:137]
	v_lshl_add_u64 v[136:137], v[68:69], 0, v[136:137]
	s_waitcnt lgkmcnt(0)
	v_mfma_f32_16x16x32_bf16 v[32:35], v[32:35], v[148:151], 0
	v_lshl_add_u64 v[140:141], v[136:137], 0, v[64:65]
	v_lshl_add_u64 v[136:137], v[136:137], 0, v[66:67]
	ds_read_b128 v[148:151], v92 offset:64
	ds_read_b128 v[152:155], v100 offset:53312
	ds_read_b128 v[216:219], v101 offset:53312
	ds_read_b128 v[220:223], v102 offset:53312
	ds_read_b128 v[232:235], v103 offset:53312
	ds_read_b128 v[236:239], v93
	ds_read_b128 v[244:247], v94
	ds_read_b128 v[212:215], v110
	s_waitcnt lgkmcnt(6)
	v_mfma_f32_16x16x32_bf16 v[124:127], v[148:151], v[152:155], v[124:127]
	ds_read_b128 v[248:251], v95
	s_waitcnt vmcnt(16)
	v_lshlrev_b32_e32 v81, 16, v160
	s_waitcnt vmcnt(8)
	v_lshlrev_b32_e32 v83, 16, v166
	s_waitcnt lgkmcnt(6)
	v_mfma_f32_16x16x32_bf16 v[128:131], v[148:151], v[216:219], v[128:131]
	ds_read_b128 v[152:155], v96
	s_waitcnt vmcnt(4)
	v_lshlrev_b32_e32 v113, 16, v172
	v_or_b32_sdwa v118, v81, v158 dst_sel:DWORD dst_unused:UNUSED_PAD src0_sel:DWORD src1_sel:WORD_0
	s_waitcnt lgkmcnt(6)
	v_mfma_f32_16x16x32_bf16 v[132:135], v[148:151], v[220:223], v[132:135]
	ds_read_b128 v[216:219], v93 offset:64
	v_lshlrev_b32_e32 v81, 16, v162
	v_lshlrev_b32_e32 v82, 16, v163
	s_waitcnt lgkmcnt(6)
	v_mfma_f32_16x16x32_bf16 v[32:35], v[148:151], v[232:235], v[32:35]
	ds_read_b128 v[220:223], v94 offset:64
	v_or_b32_sdwa v117, v83, v164 dst_sel:DWORD dst_unused:UNUSED_PAD src0_sel:DWORD src1_sel:WORD_0
	v_lshlrev_b32_e32 v83, 16, v168
	ds_read_b128 v[148:151], v110 offset:64
	s_waitcnt lgkmcnt(5)
	v_mfma_f32_16x16x32_bf16 v[124:127], v[212:215], v[236:239], v[124:127]
	ds_read_b128 v[232:235], v95 offset:64
	v_lshlrev_b32_e32 v112, 16, v169
	v_or_b32_sdwa v116, v113, v170 dst_sel:DWORD dst_unused:UNUSED_PAD src0_sel:DWORD src1_sel:WORD_0
	s_waitcnt lgkmcnt(6)
	v_mfma_f32_16x16x32_bf16 v[128:131], v[212:215], v[244:247], v[128:131]
	ds_read_b128 v[236:239], v96 offset:64
	s_waitcnt vmcnt(3)
	v_lshlrev_b32_e32 v113, 16, v174
	s_waitcnt vmcnt(2)
	v_lshlrev_b32_e32 v114, 16, v175
	s_waitcnt lgkmcnt(6)
	v_mfma_f32_16x16x32_bf16 v[132:135], v[212:215], v[248:251], v[132:135]
	ds_read_b128 v[244:247], v93 offset:128
	s_waitcnt vmcnt(0)
	v_lshlrev_b32_e32 v122, 16, v177
	s_sub_i32 s69, s69, 64
	s_waitcnt lgkmcnt(6)
	v_mfma_f32_16x16x32_bf16 v[32:35], v[212:215], v[152:155], v[32:35]
	ds_read_b128 v[248:251], v94 offset:128
	s_add_i32 s67, s67, 1
	v_or_b32_sdwa v76, v76, v147 dst_sel:DWORD dst_unused:UNUSED_PAD src0_sel:DWORD src1_sel:WORD_0
	ds_read_b128 v[212:215], v110 offset:128
	s_waitcnt lgkmcnt(5)
; __device__ __forceinline__ bf16_t f2bf(float f) { return (bf16_t)(cvt_pk_bf16(f, 0.f) & 0xffffu); }
; __device__ __forceinline__ void hg2_unit(KP p, int u, unsigned char* shm, int tid) {
;     ...
;       for (int ks = 0; ks < 4; ++ks) {
;         const bf16x8 a = *(const bf16x8*)(QIN + (mt * 16 + fr) * 136 + ks * 32 + fq * 8);
; #pragma unroll
;         for (int x = 0; x < 4; ++x) { const bf16x8 b = *(const bf16x8*)(ST + ((nb + x) * 16 + fr) * 136 + ks * 32 + fq * 8); oacc[x] = __builtin_amdgcn_mfma_f32_16x16x32_bf16(a, b, oacc[x], 0, 0, 0); }
;       }
; #pragma unroll
;       for (int j = 0; j < 4; ++j) {
;         const int sp = n * 64 + mt * 16 + fq * 4 + j; const int t = d ? (SEQ - 1 - sp) : sp;
; #pragma unroll
;         for (int x = 0; x < 4; ++x) OF[(size_t)t * 1024 + (nb + x) * 16 + fr] = f2bf(oacc[x][j]);
;       }
	v_mfma_f32_16x16x32_bf16 v[124:127], v[148:151], v[216:219], v[124:127]
	ds_read_b128 v[152:155], v95 offset:128
	v_or_b32_sdwa v81, v81, v159 dst_sel:DWORD dst_unused:UNUSED_PAD src0_sel:DWORD src1_sel:WORD_0
	v_or_b32_sdwa v82, v82, v161 dst_sel:DWORD dst_unused:UNUSED_PAD src0_sel:DWORD src1_sel:WORD_0
	s_waitcnt lgkmcnt(6)
	v_mfma_f32_16x16x32_bf16 v[128:131], v[148:151], v[220:223], v[128:131]
	ds_read_b128 v[216:219], v96 offset:128
	v_or_b32_sdwa v83, v83, v165 dst_sel:DWORD dst_unused:UNUSED_PAD src0_sel:DWORD src1_sel:WORD_0
	v_or_b32_sdwa v112, v112, v167 dst_sel:DWORD dst_unused:UNUSED_PAD src0_sel:DWORD src1_sel:WORD_0
	s_waitcnt lgkmcnt(6)
	v_mfma_f32_16x16x32_bf16 v[132:135], v[148:151], v[232:235], v[132:135]
	ds_read_b128 v[220:223], v93 offset:192
	v_or_b32_sdwa v113, v113, v171 dst_sel:DWORD dst_unused:UNUSED_PAD src0_sel:DWORD src1_sel:WORD_0
	v_or_b32_sdwa v114, v114, v173 dst_sel:DWORD dst_unused:UNUSED_PAD src0_sel:DWORD src1_sel:WORD_0
	s_waitcnt lgkmcnt(6)
	v_mfma_f32_16x16x32_bf16 v[32:35], v[148:151], v[236:239], v[32:35]
	ds_read_b128 v[232:235], v94 offset:192
	v_or_b32_sdwa v122, v122, v176 dst_sel:DWORD dst_unused:UNUSED_PAD src0_sel:DWORD src1_sel:WORD_0
	s_cmpk_lg_i32 s69, 0xfc00
	ds_read_b128 v[148:151], v110 offset:192
	s_waitcnt lgkmcnt(5)
	v_mfma_f32_16x16x32_bf16 v[124:127], v[212:215], v[244:247], v[124:127]
	ds_read_b128 v[236:239], v95 offset:192
	s_waitcnt lgkmcnt(6)
	v_mfma_f32_16x16x32_bf16 v[128:131], v[212:215], v[248:251], v[128:131]
	s_waitcnt lgkmcnt(5)
	v_mfma_f32_16x16x32_bf16 v[132:135], v[212:215], v[152:155], v[132:135]
	s_waitcnt lgkmcnt(4)
	v_mfma_f32_16x16x32_bf16 v[32:35], v[212:215], v[216:219], v[32:35]
	s_waitcnt lgkmcnt(1)
	v_mfma_f32_16x16x32_bf16 v[124:127], v[148:151], v[220:223], v[124:127]
	s_waitcnt lgkmcnt(1)
	v_mfma_f32_16x16x32_bf16 v[128:131], v[148:151], v[232:235], v[128:131]
	s_waitcnt lgkmcnt(0)
	v_mfma_f32_16x16x32_bf16 v[132:135], v[148:151], v[236:239], v[132:135]
	ds_read_b128 v[152:155], v96 offset:192
	v_cvt_pk_bf16_f32 v124, v124, v139
	s_nop 0
	global_store_short v[140:141], v124, off
	s_waitcnt lgkmcnt(0)
	v_mfma_f32_16x16x32_bf16 v[32:35], v[148:151], v[152:155], v[32:35]
	v_cvt_pk_bf16_f32 v124, v128, v139
	global_store_short v[140:141], v124, off offset:32
	v_cvt_pk_bf16_f32 v124, v132, v139
	global_store_short v[140:141], v124, off offset:64
	v_cvt_pk_bf16_f32 v32, v32, v139
	s_nop 5
	global_store_short v[136:137], v32, off
	v_add_u32_e32 v32, 1, v71
	v_add_u32_e32 v124, 0x3ffe, v123
	v_cndmask_b32_e64 v136, v124, v32, s[36:37]
	v_ashrrev_i32_e32 v137, 31, v136
	v_lshlrev_b64 v[136:137], 11, v[136:137]
	v_lshl_add_u64 v[136:137], v[68:69], 0, v[136:137]
	v_cvt_pk_bf16_f32 v32, v125, v139
	v_lshl_add_u64 v[124:125], v[136:137], 0, v[64:65]
	global_store_short v[124:125], v32, off
	v_cvt_pk_bf16_f32 v32, v129, v139
	global_store_short v[124:125], v32, off offset:32
	v_cvt_pk_bf16_f32 v32, v133, v139
	global_store_short v[124:125], v32, off offset:64
	v_cvt_pk_bf16_f32 v124, v33, v139
	v_lshl_add_u64 v[32:33], v[136:137], 0, v[66:67]
	global_store_short v[32:33], v124, off
	v_add_u32_e32 v32, 2, v71
	v_add_u32_e32 v33, 0x3ffd, v123
	v_cndmask_b32_e64 v32, v33, v32, s[36:37]
	v_ashrrev_i32_e32 v33, 31, v32
	v_lshlrev_b64 v[32:33], 11, v[32:33]
	v_lshl_add_u64 v[32:33], v[68:69], 0, v[32:33]
	v_cvt_pk_bf16_f32 v126, v126, v139
	v_lshl_add_u64 v[124:125], v[32:33], 0, v[64:65]
	global_store_short v[124:125], v126, off
	v_cvt_pk_bf16_f32 v126, v130, v139
	v_lshl_add_u64 v[32:33], v[32:33], 0, v[66:67]
	global_store_short v[124:125], v126, off offset:32
	v_cvt_pk_bf16_f32 v126, v134, v139
	global_store_short v[124:125], v126, off offset:64
	v_cvt_pk_bf16_f32 v34, v34, v139
	global_store_short v[32:33], v34, off
	v_add_u32_e32 v32, 3, v71
	v_add_u32_e32 v33, 0x3ffc, v123
	v_cndmask_b32_e64 v32, v33, v32, s[36:37]
	v_ashrrev_i32_e32 v33, 31, v32
	v_lshlrev_b64 v[32:33], 11, v[32:33]
	v_lshl_add_u64 v[32:33], v[68:69], 0, v[32:33]
	v_cvt_pk_bf16_f32 v34, v127, v139
	v_lshl_add_u64 v[124:125], v[32:33], 0, v[64:65]
	global_store_short v[124:125], v34, off
	v_cvt_pk_bf16_f32 v34, v131, v139
	global_store_short v[124:125], v34, off offset:32
	v_cvt_pk_bf16_f32 v34, v135, v139
	global_store_short v[124:125], v34, off offset:64
	v_cvt_pk_bf16_f32 v34, v35, v139
	v_lshl_add_u64 v[32:33], v[32:33], 0, v[66:67]
	global_store_short v[32:33], v34, off
	ds_read_b128 v[32:35], v104
	v_add_u32_e32 v71, 64, v71
	s_waitcnt lgkmcnt(0)
; __device__ __forceinline__ unsigned cvt_pk_bf16(float lo, float hi) { unsigned r; asm volatile("v_cvt_pk_bf16_f32 %0, %1, %2" : "=v"(r) : "v"(lo), "v"(hi)); return r; }
; __device__ __forceinline__ void hg_state_update(f32x4 (&Sacc)[8], unsigned char* shm, int wv, int fr, int fq) {
;     ...
;   float dc[4];
; #pragma unroll
;   for (int j = 0; j < 4; ++j) dc[j] = DEC[16 * wv + fq * 4 + j];
; #pragma unroll
;   for (int nt = 0; nt < 8; ++nt)
; #pragma unroll
;     for (int j = 0; j < 4; ++j) Sacc[nt][j] *= dc[j];
; #pragma unroll
;   for (int ks = 0; ks < 2; ++ks) {
;     const bf16x8 a = *(const bf16x8*)(KST + (16 * wv + fr) * 72 + ks * 32 + fq * 8);
; #pragma unroll
;     for (int nt = 0; nt < 8; ++nt) {
;       const bf16x8 b = *(const bf16x8*)(VT + (nt * 16 + fr) * 72 + ks * 32 + fq * 8);
;       Sacc[nt] = __builtin_amdgcn_mfma_f32_16x16x32_bf16(a, b, Sacc[nt], 0, 0, 0);
;     }
;   }
; }
; __device__ __forceinline__ void hg_write_st(const f32x4 (&Sacc)[8], unsigned char* shm, int wv, int fr, int fq) {
;   bf16_t* ST = (bf16_t*)(shm + HG_ST);
; #pragma unroll
;   for (int nt = 0; nt < 8; ++nt) {
;     u32x2 w; w.x = cvt_pk_bf16(Sacc[nt][0], Sacc[nt][1]); w.y = cvt_pk_bf16(Sacc[nt][2], Sacc[nt][3]);
;     *(u32x2*)(ST + (nt * 16 + fr) * 136 + 16 * wv + fq * 4) = w;
	v_pk_mul_f32 v[0:1], v[0:1], v[32:33]
	v_pk_mul_f32 v[4:5], v[4:5], v[32:33]
	v_pk_mul_f32 v[8:9], v[8:9], v[32:33]
	v_pk_mul_f32 v[2:3], v[2:3], v[34:35]
	v_pk_mul_f32 v[6:7], v[6:7], v[34:35]
	v_pk_mul_f32 v[10:11], v[10:11], v[34:35]
	v_pk_mul_f32 v[12:13], v[12:13], v[32:33]
	v_pk_mul_f32 v[14:15], v[14:15], v[34:35]
	v_pk_mul_f32 v[16:17], v[16:17], v[32:33]
	v_pk_mul_f32 v[18:19], v[18:19], v[34:35]
	v_pk_mul_f32 v[20:21], v[20:21], v[32:33]
	v_pk_mul_f32 v[22:23], v[22:23], v[34:35]
	v_pk_mul_f32 v[24:25], v[24:25], v[32:33]
	v_pk_mul_f32 v[26:27], v[26:27], v[34:35]
	v_pk_mul_f32 v[28:29], v[28:29], v[32:33]
	v_pk_mul_f32 v[30:31], v[30:31], v[34:35]
	ds_read_b128 v[32:35], v105 offset:34816
	ds_read_b128 v[124:127], v106 offset:53248
	ds_read_b128 v[216:219], v106 offset:55552
	ds_read_b128 v[220:223], v106 offset:57856
	ds_read_b128 v[232:235], v106 offset:60160
	ds_read_b128 v[236:239], v106 offset:62464
	ds_read_b128 v[244:247], v106 offset:64768
	ds_read_b128 v[212:215], v105 offset:34880
	s_waitcnt lgkmcnt(6)
	v_mfma_f32_16x16x32_bf16 v[0:3], v[32:35], v[124:127], v[0:3]
	ds_read_b128 v[248:251], v107 offset:53248
	s_waitcnt lgkmcnt(6)
	v_mfma_f32_16x16x32_bf16 v[4:7], v[32:35], v[216:219], v[4:7]
	ds_read_b128 v[124:127], v108 offset:53248
	s_waitcnt lgkmcnt(6)
	v_mfma_f32_16x16x32_bf16 v[8:11], v[32:35], v[220:223], v[8:11]
	ds_read_b128 v[216:219], v106 offset:53312
	s_waitcnt lgkmcnt(6)
	v_mfma_f32_16x16x32_bf16 v[12:15], v[32:35], v[232:235], v[12:15]
	ds_read_b128 v[220:223], v106 offset:55616
	s_waitcnt lgkmcnt(6)
	v_mfma_f32_16x16x32_bf16 v[16:19], v[32:35], v[236:239], v[16:19]
	ds_read_b128 v[232:235], v106 offset:57920
	s_waitcnt lgkmcnt(6)
	v_mfma_f32_16x16x32_bf16 v[20:23], v[32:35], v[244:247], v[20:23]
	ds_read_b128 v[236:239], v106 offset:60224
	s_waitcnt lgkmcnt(5)
	v_mfma_f32_16x16x32_bf16 v[24:27], v[32:35], v[248:251], v[24:27]
	ds_read_b128 v[244:247], v106 offset:62528
	s_waitcnt lgkmcnt(5)
	v_mfma_f32_16x16x32_bf16 v[28:31], v[32:35], v[124:127], v[28:31]
	ds_read_b128 v[248:251], v106 offset:64832
	s_waitcnt lgkmcnt(5)
	v_mfma_f32_16x16x32_bf16 v[0:3], v[212:215], v[216:219], v[0:3]
	ds_read_b128 v[124:127], v107 offset:53312
	s_waitcnt lgkmcnt(5)
	v_mfma_f32_16x16x32_bf16 v[4:7], v[212:215], v[220:223], v[4:7]
	ds_read_b128 v[216:219], v108 offset:53312
	s_waitcnt lgkmcnt(5)
	v_mfma_f32_16x16x32_bf16 v[8:11], v[212:215], v[232:235], v[8:11]
	s_waitcnt lgkmcnt(4)
	v_mfma_f32_16x16x32_bf16 v[12:15], v[212:215], v[236:239], v[12:15]
	s_waitcnt lgkmcnt(3)
	v_mfma_f32_16x16x32_bf16 v[16:19], v[212:215], v[244:247], v[16:19]
	s_waitcnt lgkmcnt(2)
	v_mfma_f32_16x16x32_bf16 v[20:23], v[212:215], v[248:251], v[20:23]
	s_waitcnt lgkmcnt(1)
	v_mfma_f32_16x16x32_bf16 v[24:27], v[212:215], v[124:127], v[24:27]
	s_waitcnt lgkmcnt(0)
	v_mfma_f32_16x16x32_bf16 v[28:31], v[212:215], v[216:219], v[28:31]
	s_waitcnt lgkmcnt(0)
	s_barrier
	v_cvt_pk_bf16_f32 v32, v0, v1
	v_cvt_pk_bf16_f32 v33, v2, v3
	ds_write_b64 v109, v[32:33]
	v_cvt_pk_bf16_f32 v32, v4, v5
	v_cvt_pk_bf16_f32 v33, v6, v7
	ds_write_b64 v109, v[32:33] offset:4352
	v_cvt_pk_bf16_f32 v32, v8, v9
	v_cvt_pk_bf16_f32 v33, v10, v11
	ds_write_b64 v109, v[32:33] offset:8704
	v_cvt_pk_bf16_f32 v32, v12, v13
	v_cvt_pk_bf16_f32 v33, v14, v15
	ds_write_b64 v109, v[32:33] offset:13056
	v_cvt_pk_bf16_f32 v32, v16, v17
	v_cvt_pk_bf16_f32 v33, v18, v19
	ds_write_b64 v109, v[32:33] offset:17408
	v_cvt_pk_bf16_f32 v32, v20, v21
	v_cvt_pk_bf16_f32 v33, v22, v23
	ds_write_b64 v109, v[32:33] offset:21760
	v_cvt_pk_bf16_f32 v32, v24, v25
	v_cvt_pk_bf16_f32 v33, v26, v27
	ds_write_b64 v109, v[32:33] offset:26112
	v_cvt_pk_bf16_f32 v32, v28, v29
	v_cvt_pk_bf16_f32 v33, v30, v31
	ds_write_b64 v109, v[32:33] offset:30464
	s_cbranch_scc0 .LBB0_71

; __device__ __forceinline__ void final_norm(float* x, const float* gam, int tid) {
;   const int lane = tid & 63; const int gw = blockIdx.x * 8 + (tid >> 6), nw = gridDim.x * 8;
;   for (int r = gw; r < SEQ; r += nw) {
;     f32x4* xr = (f32x4*)(x + (size_t)r * DM) + lane;
;     f32x4 v[8]; float ss = 0.f;
; #pragma unroll
;     for (int j = 0; j < 8; ++j) { v[j] = xr[64 * j]; ss += v[j][0] * v[j][0] + v[j][1] * v[j][1] + v[j][2] * v[j][2] + v[j][3] * v[j][3]; }
;     const float rstd = rsqrtf(wave_sum(ss) * (1.0f / DM) + 1e-6f);
; #pragma unroll
;     for (int j = 0; j < 8; ++j) xr[64 * j] = v[j] * rstd * *(const f32x4*)(gam + 4 * (lane + 64 * j));
;   }
; }
.LBB0_459:
	s_andn2_b64 vcc, exec, s[2:3]
	s_cbranch_vccnz .LBB0_464
	v_ashrrev_i32_e32 v0, 6, v146
	v_readlane_b32 s2, v253, 19
	s_nop 1
	v_add_u32_e32 v0, s2, v0
	s_movk_i32 s2, 0x4000
	v_cmp_gt_i32_e32 vcc, s2, v0
	s_and_saveexec_b64 s[2:3], vcc
	v_readlane_b32 s8, v253, 51
	v_readlane_b32 s9, v253, 52
	s_cbranch_execz .LBB0_463
	v_readlane_b32 s10, v254, 9
	v_readlane_b32 s11, v254, 10
	s_load_dwordx4 s[4:7], s[10:11], 0x100
	v_lshlrev_b32_e32 v1, 4, v229
	v_and_b32_e32 v138, 0x3f0, v1
	v_ashrrev_i32_e32 v1, 31, v0
	v_lshlrev_b64 v[12:13], 13, v[0:1]
	s_waitcnt lgkmcnt(0)
	v_lshl_add_u64 v[2:3], s[4:5], 0, v[138:139]
	s_mov_b64 s[4:5], 0x1400
	v_lshl_add_u64 v[6:7], v[2:3], 0, s[4:5]
	s_mov_b64 s[4:5], 0x1800
	v_or_b32_e32 v12, v12, v138
	s_mov_b64 s[10:11], 0x1000
	v_lshl_add_u64 v[8:9], v[2:3], 0, s[4:5]
	s_mov_b64 s[4:5], 0x1c00
	v_lshl_add_u64 v[12:13], s[6:7], 0, v[12:13]
	v_lshl_add_u64 v[4:5], v[2:3], 0, s[10:11]
	v_lshl_add_u64 v[10:11], v[2:3], 0, s[4:5]
	v_lshl_add_u64 v[12:13], v[12:13], 0, s[10:11]
	s_mov_b64 s[4:5], 0
	global_load_dwordx4 v[72:75], v[2:3], off
	global_load_dwordx4 v[76:79], v[2:3], off offset:1024
	global_load_dwordx4 v[80:83], v[2:3], off offset:2048
	global_load_dwordx4 v[84:87], v[2:3], off offset:3072
	global_load_dwordx4 v[88:91], v[4:5], off
	global_load_dwordx4 v[92:95], v[6:7], off
	global_load_dwordx4 v[96:99], v[8:9], off
	global_load_dwordx4 v[100:103], v[10:11], off
	v_mbcnt_lo_u32_b32 v1, -1, 0
	v_mbcnt_hi_u32_b32 v1, -1, v1
	v_lshlrev_b32_e32 v66, 2, v1
	v_xor_b32_e32 v104, 4, v66
	v_xor_b32_e32 v105, 8, v66
	v_xor_b32_e32 v106, 16, v66
	v_xor_b32_e32 v107, 32, v66
	v_xor_b32_e32 v108, 64, v66
	v_xor_b32_e32 v109, 0x80, v66
.Lfn_loop:
	global_load_dwordx4 v[14:17], v[12:13], off offset:-4096
	global_load_dwordx4 v[18:21], v[12:13], off offset:-3072
	global_load_dwordx4 v[22:25], v[12:13], off offset:-2048
	global_load_dwordx4 v[26:29], v[12:13], off offset:-1024
	global_load_dwordx4 v[30:33], v[12:13], off
	global_load_dwordx4 v[34:37], v[12:13], off offset:1024
	global_load_dwordx4 v[38:41], v[12:13], off offset:2048
	global_load_dwordx4 v[42:45], v[12:13], off offset:3072
	v_add_u32_e32 v0, s82, v0
	s_waitcnt vmcnt(7)
	v_pk_mul_f32 v[50:51], v[14:15], v[14:15]
	v_pk_fma_f32 v[50:51], v[16:17], v[16:17], v[50:51]
	s_waitcnt vmcnt(6)
	v_pk_mul_f32 v[52:53], v[18:19], v[18:19]
	v_pk_fma_f32 v[52:53], v[20:21], v[20:21], v[52:53]
	s_waitcnt vmcnt(5)
	v_pk_mul_f32 v[54:55], v[22:23], v[22:23]
	v_pk_fma_f32 v[54:55], v[24:25], v[24:25], v[54:55]
	s_waitcnt vmcnt(4)
	v_pk_mul_f32 v[56:57], v[26:27], v[26:27]
	v_pk_fma_f32 v[56:57], v[28:29], v[28:29], v[56:57]
	s_waitcnt vmcnt(3)
	v_pk_mul_f32 v[58:59], v[30:31], v[30:31]
	v_pk_fma_f32 v[58:59], v[32:33], v[32:33], v[58:59]
	s_waitcnt vmcnt(2)
	v_pk_mul_f32 v[60:61], v[34:35], v[34:35]
	v_pk_fma_f32 v[60:61], v[36:37], v[36:37], v[60:61]
	s_waitcnt vmcnt(1)
	v_pk_mul_f32 v[62:63], v[38:39], v[38:39]
	v_pk_fma_f32 v[62:63], v[40:41], v[40:41], v[62:63]
	s_waitcnt vmcnt(0)
	v_pk_mul_f32 v[64:65], v[42:43], v[42:43]
	v_pk_fma_f32 v[64:65], v[44:45], v[44:45], v[64:65]
	v_pk_add_f32 v[50:51], v[50:51], v[52:53]
	v_pk_add_f32 v[54:55], v[54:55], v[56:57]
	v_pk_add_f32 v[58:59], v[58:59], v[60:61]
	v_pk_add_f32 v[62:63], v[62:63], v[64:65]
	v_pk_add_f32 v[50:51], v[50:51], v[54:55]
	v_pk_add_f32 v[58:59], v[58:59], v[62:63]
	v_pk_add_f32 v[50:51], v[50:51], v[58:59]
	v_add_f32_e32 v50, v50, v51
	ds_bpermute_b32 v51, v104, v50
	s_waitcnt lgkmcnt(0)
	v_add_f32_e32 v50, v50, v51
	ds_bpermute_b32 v51, v105, v50
	s_waitcnt lgkmcnt(0)
	v_add_f32_e32 v50, v50, v51
	ds_bpermute_b32 v51, v106, v50
	s_waitcnt lgkmcnt(0)
	v_add_f32_e32 v50, v50, v51
	ds_bpermute_b32 v51, v107, v50
	s_waitcnt lgkmcnt(0)
	v_add_f32_e32 v50, v50, v51
	ds_bpermute_b32 v51, v108, v50
	s_waitcnt lgkmcnt(0)
	v_add_f32_e32 v50, v50, v51
	ds_bpermute_b32 v51, v109, v50
	s_waitcnt lgkmcnt(0)
	v_add_f32_e32 v50, v50, v51
	v_fmamk_f32 v1, v50, 0x3a000000, v228
	v_mul_f32_e32 v50, 0x4b800000, v1
	v_cmp_gt_f32_e32 vcc, s67, v1
	s_nop 1
	v_cndmask_b32_e32 v1, v1, v50, vcc
	v_rsq_f32_e32 v1, v1
	s_nop 0
	v_mul_f32_e32 v50, 0x45800000, v1
	v_cndmask_b32_e32 v50, v1, v50, vcc
	v_cmp_lt_i32_e32 vcc, s51, v0
	s_or_b64 s[4:5], vcc, s[4:5]
	s_waitcnt vmcnt(0)
	v_pk_mul_f32 v[14:15], v[14:15], v[50:51] op_sel_hi:[1,0]
	v_pk_mul_f32 v[16:17], v[16:17], v[50:51] op_sel_hi:[1,0]
	v_pk_mul_f32 v[14:15], v[72:73], v[14:15]
	v_pk_mul_f32 v[16:17], v[74:75], v[16:17]
	global_store_dwordx4 v[12:13], v[14:17], off offset:-4096
	v_pk_mul_f32 v[18:19], v[18:19], v[50:51] op_sel_hi:[1,0]
	v_pk_mul_f32 v[20:21], v[20:21], v[50:51] op_sel_hi:[1,0]
	v_pk_mul_f32 v[18:19], v[76:77], v[18:19]
	v_pk_mul_f32 v[20:21], v[78:79], v[20:21]
	global_store_dwordx4 v[12:13], v[18:21], off offset:-3072
	v_pk_mul_f32 v[22:23], v[22:23], v[50:51] op_sel_hi:[1,0]
	v_pk_mul_f32 v[24:25], v[24:25], v[50:51] op_sel_hi:[1,0]
	v_pk_mul_f32 v[22:23], v[80:81], v[22:23]
	v_pk_mul_f32 v[24:25], v[82:83], v[24:25]
	global_store_dwordx4 v[12:13], v[22:25], off offset:-2048
	v_pk_mul_f32 v[26:27], v[26:27], v[50:51] op_sel_hi:[1,0]
	v_pk_mul_f32 v[28:29], v[28:29], v[50:51] op_sel_hi:[1,0]
	v_pk_mul_f32 v[26:27], v[84:85], v[26:27]
	v_pk_mul_f32 v[28:29], v[86:87], v[28:29]
	global_store_dwordx4 v[12:13], v[26:29], off offset:-1024
	v_pk_mul_f32 v[30:31], v[30:31], v[50:51] op_sel_hi:[1,0]
	v_pk_mul_f32 v[32:33], v[32:33], v[50:51] op_sel_hi:[1,0]
	v_pk_mul_f32 v[30:31], v[88:89], v[30:31]
	v_pk_mul_f32 v[32:33], v[90:91], v[32:33]
	global_store_dwordx4 v[12:13], v[30:33], off
	v_pk_mul_f32 v[34:35], v[34:35], v[50:51] op_sel_hi:[1,0]
	v_pk_mul_f32 v[36:37], v[36:37], v[50:51] op_sel_hi:[1,0]
	v_pk_mul_f32 v[34:35], v[92:93], v[34:35]
	v_pk_mul_f32 v[36:37], v[94:95], v[36:37]
	global_store_dwordx4 v[12:13], v[34:37], off offset:1024
	v_pk_mul_f32 v[38:39], v[38:39], v[50:51] op_sel_hi:[1,0]
	v_pk_mul_f32 v[40:41], v[40:41], v[50:51] op_sel_hi:[1,0]
	v_pk_mul_f32 v[38:39], v[96:97], v[38:39]
	v_pk_mul_f32 v[40:41], v[98:99], v[40:41]
	global_store_dwordx4 v[12:13], v[38:41], off offset:2048
	v_pk_mul_f32 v[42:43], v[42:43], v[50:51] op_sel_hi:[1,0]
	v_pk_mul_f32 v[44:45], v[44:45], v[50:51] op_sel_hi:[1,0]
	v_pk_mul_f32 v[42:43], v[100:101], v[42:43]
	v_pk_mul_f32 v[44:45], v[102:103], v[44:45]
	global_store_dwordx4 v[12:13], v[42:45], off offset:3072
	s_nop 1
	v_lshl_add_u64 v[12:13], v[12:13], 0, s[8:9]
	s_andn2_b64 exec, exec, s[4:5]
	s_cbranch_execnz .Lfn_loop
